# dense-GQA attention loop: dropped the per-step copies of the running -max accumulator init and halved the 64-bit VALU adds for the LDS-DMA addresses
# baseline (speedup 1.0000x reference)
.LBB0_399:
	s_add_i32 s34, s56, 0xfffc0000
	s_add_i32 s30, s55, -1
	s_and_b32 s34, s34, 0xf00000
	s_and_b32 s30, s30, 3
	s_lshl_b32 s78, s34, 1
	s_add_i32 s54, s29, 0
	s_mul_i32 s58, s30, 0x38000
	s_mov_b32 s59, s79
	s_add_u32 s98, s78, s58
	s_addc_u32 s99, s79, s79
	s_add_i32 s34, s54, s5
	v_lshl_add_u64 v[34:35], v[116:117], 0, s[98:99]
	s_mov_b32 m0, s34
	s_add_i32 s35, s34, 0x2000
	global_load_lds_dwordx4 v[34:35], off
	v_lshl_add_u64 v[34:35], v[118:119], 0, s[98:99]
	s_mov_b32 m0, s35
	s_mov_b32 s30, s27
	global_load_lds_dwordx4 v[34:35], off
	s_mov_b32 s27, s72
	s_add_i32 s53, s30, 0
	v_add_u32_e32 v0, s53, v126
	ds_read_b128 v[34:37], v0
	ds_read_b128 v[38:41], v0 offset:2048
	v_exp_f32_e32 v145, v66
	v_exp_f32_e32 v146, v67
	v_exp_f32_e32 v147, v68
	v_exp_f32_e32 v148, v69
	v_exp_f32_e32 v149, v70
	v_exp_f32_e32 v150, v71
	v_exp_f32_e32 v151, v72
	s_waitcnt lgkmcnt(0)
	v_mfma_f32_32x32x16_bf16 v[82:97], v[34:37], v[110:113], v[50:65]
	ds_read_b128 v[34:37], v0 offset:4096
	v_exp_f32_e32 v152, v73
	v_exp_f32_e32 v153, v74
	v_exp_f32_e32 v154, v75
	v_exp_f32_e32 v155, v76
	v_exp_f32_e32 v156, v77
	v_exp_f32_e32 v157, v78
	v_mfma_f32_32x32x16_bf16 v[82:97], v[38:41], v[106:109], v[82:97]
	ds_read_b128 v[38:41], v0 offset:6144
	v_exp_f32_e32 v158, v79
	v_exp_f32_e32 v159, v80
	v_exp_f32_e32 v160, v81
	s_waitcnt lgkmcnt(0)
	v_mfma_f32_32x32x16_bf16 v[82:97], v[34:37], v[102:105], v[82:97]
	v_add_f32_e32 v34, v129, v131
	v_add_f32_e32 v66, v132, v34
	ds_read_b128 v[34:37], v0 offset:512
	ds_read_b128 v[42:45], v0 offset:2560
	ds_read_b128 v[46:49], v0 offset:4608
	v_mfma_f32_32x32x16_bf16 v[82:97], v[38:41], v[98:101], v[82:97]
	ds_read_b128 v[38:41], v0 offset:6656
	v_add_f32_e32 v0, v135, v66
	v_add_f32_e32 v0, v136, v0
	v_add_f32_e32 v0, v139, v0
	v_add_f32_e32 v0, v140, v0
	v_add_f32_e32 v0, v143, v0
	v_add_f32_e32 v0, v130, v0
	s_waitcnt lgkmcnt(0)
	v_mfma_f32_32x32x16_bf16 v[66:81], v[34:37], v[110:113], v[50:65]
	v_add_f32_e32 v0, v133, v0
	v_add_f32_e32 v0, v134, v0
	v_add_f32_e32 v0, v137, v0
	v_add_f32_e32 v0, v138, v0
	v_add_f32_e32 v0, v141, v0
	v_add_f32_e32 v0, v142, v0
	v_add_f32_e32 v0, v144, v0
	v_mfma_f32_32x32x16_bf16 v[66:81], v[42:45], v[106:109], v[66:81]
	v_add_f32_e32 v0, v145, v0
	v_add_f32_e32 v0, v146, v0
	v_add_f32_e32 v0, v147, v0
	v_add_f32_e32 v0, v148, v0
	v_add_f32_e32 v0, v149, v0
	v_add_f32_e32 v0, v150, v0
	v_add_f32_e32 v0, v151, v0
	v_mfma_f32_32x32x16_bf16 v[66:81], v[46:49], v[102:105], v[66:81]
	v_add_f32_e32 v0, v152, v0
	v_add_f32_e32 v0, v153, v0
	v_add_f32_e32 v0, v154, v0
	v_add_f32_e32 v0, v155, v0
	v_add_f32_e32 v0, v156, v0
	v_add_f32_e32 v0, v157, v0
	v_add_f32_e32 v0, v158, v0
	v_mfma_f32_32x32x16_bf16 v[66:81], v[38:41], v[98:101], v[66:81]
	v_cvt_pk_bf16_f32 v34, v129, v131
	v_add_f32_e32 v161, v159, v0
	v_cvt_pk_bf16_f32 v35, v132, v135
	v_cvt_pk_bf16_f32 v36, v136, v139
	v_cvt_pk_bf16_f32 v37, v140, v143
	v_cvt_pk_bf16_f32 v38, v130, v133
	v_cvt_pk_bf16_f32 v39, v134, v137
	v_cvt_pk_bf16_f32 v40, v138, v141
	v_cvt_pk_bf16_f32 v41, v142, v144
	v_cvt_pk_bf16_f32 v42, v145, v146
	v_cvt_pk_bf16_f32 v43, v147, v148
	v_cvt_pk_bf16_f32 v44, v149, v150
	v_cvt_pk_bf16_f32 v45, v151, v152
	v_cvt_pk_bf16_f32 v46, v153, v154
	v_cvt_pk_bf16_f32 v47, v155, v156
	v_cvt_pk_bf16_f32 v48, v157, v158
	v_cvt_pk_bf16_f32 v49, v159, v160
	s_add_i32 s57, s72, 0
	v_add_u32_e32 v0, s57, v125
	ds_read_b64_tr_b16 v[130:131], v0 offset:8192
	ds_read_b64_tr_b16 v[132:133], v0 offset:8704
	ds_read_b64_tr_b16 v[134:135], v0 offset:12288
	v_max_f32_e32 v129, v67, v67
	s_waitcnt lgkmcnt(1)
	v_mfma_f32_32x32x16_bf16 v[18:33], v[130:133], v[34:37], v[18:33]
	ds_read_b64_tr_b16 v[136:137], v0 offset:12800
	ds_read_b64_tr_b16 v[130:131], v0 offset:9216
	s_waitcnt lgkmcnt(1)
	v_mfma_f32_32x32x16_bf16 v[2:17], v[134:137], v[34:37], v[2:17]
	ds_read_b64_tr_b16 v[132:133], v0 offset:9728
	ds_read_b64_tr_b16 v[34:35], v0 offset:13312
	s_waitcnt lgkmcnt(1)
	v_mfma_f32_32x32x16_bf16 v[18:33], v[130:133], v[38:41], v[18:33]
	ds_read_b64_tr_b16 v[36:37], v0 offset:13824
	ds_read_b64_tr_b16 v[130:131], v0 offset:10240
	s_waitcnt lgkmcnt(1)
	v_mfma_f32_32x32x16_bf16 v[2:17], v[34:37], v[38:41], v[2:17]
	ds_read_b64_tr_b16 v[132:133], v0 offset:10752
	ds_read_b64_tr_b16 v[34:35], v0 offset:11264
	ds_read_b64_tr_b16 v[36:37], v0 offset:11776
	ds_read_b64_tr_b16 v[38:39], v0 offset:14336
	ds_read_b64_tr_b16 v[40:41], v0 offset:14848
	ds_read_b64_tr_b16 v[134:135], v0 offset:15360
	ds_read_b64_tr_b16 v[136:137], v0 offset:15872
	s_waitcnt lgkmcnt(6)
	v_mfma_f32_32x32x16_bf16 v[18:33], v[130:133], v[42:45], v[18:33]
	v_max_f32_e32 v130, v83, v83
	v_max_f32_e32 v129, v130, v129
	v_max3_f32 v130, v82, v66, v84
	v_max3_f32 v129, v129, v85, v69
	v_max3_f32 v130, v130, v68, v86
	v_max3_f32 v129, v129, v87, v71
	s_waitcnt lgkmcnt(2)
	v_mfma_f32_32x32x16_bf16 v[2:17], v[38:41], v[42:45], v[2:17]
	v_max3_f32 v38, v130, v70, v88
	v_max3_f32 v39, v129, v89, v73
	v_max3_f32 v38, v38, v72, v90
	v_max3_f32 v39, v39, v91, v75
	v_max3_f32 v38, v38, v74, v92
	v_max3_f32 v39, v39, v93, v77
	v_max3_f32 v38, v38, v76, v94
	v_mfma_f32_32x32x16_bf16 v[18:33], v[34:37], v[46:49], v[18:33]
	v_max3_f32 v34, v39, v95, v79
	v_max3_f32 v35, v38, v78, v96
	v_max3_f32 v34, v34, v97, v81
	v_add_f32_e32 v36, v160, v161
	v_max3_f32 v34, v35, v80, v34
	v_add_f32_e32 v128, v128, v36
	v_cmp_lt_f32_e32 vcc, s33, v34
	s_waitcnt lgkmcnt(0)
	v_mfma_f32_32x32x16_bf16 v[2:17], v[134:137], v[46:49], v[2:17]
	s_cbranch_vccz .LBB0_401
	v_mov_b32_e32 v35, v34
	s_nop 1
	v_permlane32_swap_b32 v34, v35
	s_nop 1
	s_nop 0
	v_max3_f32 v36, v34, v35, 0
	v_exp_f32_e64 v38, -v36
	v_add_f32_e32 v127, v127, v36
	v_xor_b32_e32 v34, 0x80000000, v127
	v_pk_add_f32 v[82:83], v[82:83], v[36:37] op_sel_hi:[1,0] neg_lo:[0,1] neg_hi:[0,1]
	v_pk_add_f32 v[66:67], v[66:67], v[36:37] op_sel_hi:[1,0] neg_lo:[0,1] neg_hi:[0,1]
	v_pk_add_f32 v[84:85], v[84:85], v[36:37] op_sel_hi:[1,0] neg_lo:[0,1] neg_hi:[0,1]
	v_pk_add_f32 v[68:69], v[68:69], v[36:37] op_sel_hi:[1,0] neg_lo:[0,1] neg_hi:[0,1]
	v_pk_add_f32 v[86:87], v[86:87], v[36:37] op_sel_hi:[1,0] neg_lo:[0,1] neg_hi:[0,1]
	v_pk_add_f32 v[70:71], v[70:71], v[36:37] op_sel_hi:[1,0] neg_lo:[0,1] neg_hi:[0,1]
	v_pk_add_f32 v[88:89], v[88:89], v[36:37] op_sel_hi:[1,0] neg_lo:[0,1] neg_hi:[0,1]
	v_pk_add_f32 v[72:73], v[72:73], v[36:37] op_sel_hi:[1,0] neg_lo:[0,1] neg_hi:[0,1]
	v_pk_add_f32 v[90:91], v[90:91], v[36:37] op_sel_hi:[1,0] neg_lo:[0,1] neg_hi:[0,1]
	v_pk_add_f32 v[74:75], v[74:75], v[36:37] op_sel_hi:[1,0] neg_lo:[0,1] neg_hi:[0,1]
	v_pk_add_f32 v[92:93], v[92:93], v[36:37] op_sel_hi:[1,0] neg_lo:[0,1] neg_hi:[0,1]
	v_pk_add_f32 v[76:77], v[76:77], v[36:37] op_sel_hi:[1,0] neg_lo:[0,1] neg_hi:[0,1]
	v_pk_add_f32 v[94:95], v[94:95], v[36:37] op_sel_hi:[1,0] neg_lo:[0,1] neg_hi:[0,1]
	v_pk_add_f32 v[78:79], v[78:79], v[36:37] op_sel_hi:[1,0] neg_lo:[0,1] neg_hi:[0,1]
	v_pk_add_f32 v[96:97], v[96:97], v[36:37] op_sel_hi:[1,0] neg_lo:[0,1] neg_hi:[0,1]
	v_pk_add_f32 v[80:81], v[80:81], v[36:37] op_sel_hi:[1,0] neg_lo:[0,1] neg_hi:[0,1]
	v_pk_mul_f32 v[32:33], v[32:33], v[38:39] op_sel_hi:[1,0]
	v_pk_mul_f32 v[30:31], v[30:31], v[38:39] op_sel_hi:[1,0]
	v_pk_mul_f32 v[28:29], v[28:29], v[38:39] op_sel_hi:[1,0]
	v_pk_mul_f32 v[26:27], v[26:27], v[38:39] op_sel_hi:[1,0]
	v_pk_mul_f32 v[24:25], v[24:25], v[38:39] op_sel_hi:[1,0]
	v_pk_mul_f32 v[22:23], v[22:23], v[38:39] op_sel_hi:[1,0]
	v_pk_mul_f32 v[20:21], v[20:21], v[38:39] op_sel_hi:[1,0]
	v_pk_mul_f32 v[18:19], v[18:19], v[38:39] op_sel_hi:[1,0]
	v_pk_mul_f32 v[16:17], v[16:17], v[38:39] op_sel_hi:[1,0]
	v_pk_mul_f32 v[14:15], v[14:15], v[38:39] op_sel_hi:[1,0]
	v_pk_mul_f32 v[12:13], v[12:13], v[38:39] op_sel_hi:[1,0]
	v_pk_mul_f32 v[10:11], v[10:11], v[38:39] op_sel_hi:[1,0]
	v_pk_mul_f32 v[8:9], v[8:9], v[38:39] op_sel_hi:[1,0]
	v_pk_mul_f32 v[6:7], v[6:7], v[38:39] op_sel_hi:[1,0]
	v_pk_mul_f32 v[4:5], v[4:5], v[38:39] op_sel_hi:[1,0]
	v_pk_mul_f32 v[2:3], v[2:3], v[38:39] op_sel_hi:[1,0]
	v_mul_f32_e32 v128, v128, v38
	v_mov_b32_e32 v35, v34
	v_mov_b32_e32 v36, v34
	v_mov_b32_e32 v37, v34
	v_mov_b32_e32 v38, v34
	v_mov_b32_e32 v39, v34
	v_mov_b32_e32 v40, v34
	v_mov_b32_e32 v41, v34
	v_mov_b32_e32 v42, v34
	v_mov_b32_e32 v43, v34
	v_mov_b32_e32 v44, v34
	v_mov_b32_e32 v45, v34
	v_mov_b32_e32 v46, v34
	v_mov_b32_e32 v47, v34
	v_mov_b32_e32 v48, v34
	v_mov_b32_e32 v49, v34
	v_mov_b32_e32 v50, v34
	v_mov_b32_e32 v51, v34
	v_mov_b32_e32 v52, v34
	v_mov_b32_e32 v53, v34
	v_mov_b32_e32 v54, v34
	v_mov_b32_e32 v55, v34
	v_mov_b32_e32 v56, v34
	v_mov_b32_e32 v57, v34
	v_mov_b32_e32 v58, v34
	v_mov_b32_e32 v59, v34
	v_mov_b32_e32 v60, v34
	v_mov_b32_e32 v61, v34
	v_mov_b32_e32 v62, v34
	v_mov_b32_e32 v63, v34
	v_mov_b32_e32 v64, v34
	v_mov_b32_e32 v65, v34
	s_branch .LBB0_402
.LBB0_401:
.LBB0_402:
	v_exp_f32_e32 v129, v82
	v_exp_f32_e32 v146, v83
	v_exp_f32_e32 v147, v84
	v_exp_f32_e32 v148, v85
	v_exp_f32_e32 v149, v86
	v_exp_f32_e32 v150, v87
	v_exp_f32_e32 v151, v88
	v_exp_f32_e32 v152, v89
	v_exp_f32_e32 v153, v90
	v_exp_f32_e32 v154, v91
	v_exp_f32_e32 v155, v92
	v_exp_f32_e32 v156, v93
	v_exp_f32_e32 v157, v94
	v_exp_f32_e32 v158, v95
	v_exp_f32_e32 v159, v96
	v_exp_f32_e32 v160, v97
	s_add_i32 s58, s55, 4
	s_and_b32 s59, s56, 0xf00000
	s_and_b32 s58, s58, 3
	s_lshl_b32 s78, s59, 1
	s_mul_i32 s58, s58, 0x38000
	s_mov_b32 s59, s79
	s_add_u32 s98, s78, s58
	s_addc_u32 s99, s79, s79
	s_add_i32 s60, s57, s5
	v_lshl_add_u64 v[82:83], v[116:117], 0, s[98:99]
	s_mov_b32 m0, s60
	s_waitcnt vmcnt(0)
	s_barrier
	global_load_lds_dwordx4 v[82:83], off
	v_lshl_add_u64 v[82:83], v[118:119], 0, s[98:99]
	s_add_i32 m0, s60, 0x2000
	s_nop 0
	global_load_lds_dwordx4 v[82:83], off
	v_add_u32_e32 v142, s54, v126
	ds_read_b128 v[130:133], v142
	ds_read_b128 v[134:137], v142 offset:2048
	v_exp_f32_e32 v161, v66
	v_exp_f32_e32 v162, v67
	v_exp_f32_e32 v163, v68
	v_exp_f32_e32 v164, v69
	ds_read_b128 v[66:69], v142 offset:4096
	v_exp_f32_e32 v165, v70
	v_exp_f32_e32 v166, v71
	s_waitcnt lgkmcnt(0)
	v_mfma_f32_32x32x16_bf16 v[82:97], v[130:133], v[110:113], v[50:65]
	v_exp_f32_e32 v167, v72
	v_exp_f32_e32 v168, v73
	ds_read_b128 v[70:73], v142 offset:6144
	v_exp_f32_e32 v169, v74
	v_exp_f32_e32 v170, v75
	v_exp_f32_e32 v171, v76
	v_exp_f32_e32 v172, v77
	v_mfma_f32_32x32x16_bf16 v[82:97], v[134:137], v[106:109], v[82:97]
	ds_read_b128 v[130:133], v142 offset:512
	ds_read_b128 v[134:137], v142 offset:2560
	ds_read_b128 v[138:141], v142 offset:4608
	ds_read_b128 v[142:145], v142 offset:6656
	v_exp_f32_e32 v173, v78
	v_exp_f32_e32 v174, v79
	v_exp_f32_e32 v175, v80
	v_exp_f32_e32 v176, v81
	v_mfma_f32_32x32x16_bf16 v[82:97], v[66:69], v[102:105], v[82:97]
	v_add_f32_e32 v66, v129, v146
	v_add_f32_e32 v66, v147, v66
	v_add_f32_e32 v66, v148, v66
	v_add_f32_e32 v66, v149, v66
	v_add_f32_e32 v66, v150, v66
	v_add_f32_e32 v66, v151, v66
	v_add_f32_e32 v66, v152, v66
	v_add_f32_e32 v66, v153, v66
	s_waitcnt lgkmcnt(0)
	v_mfma_f32_32x32x16_bf16 v[82:97], v[70:73], v[98:101], v[82:97]
	v_add_f32_e32 v177, v154, v66
	v_mfma_f32_32x32x16_bf16 v[66:81], v[130:133], v[110:113], v[50:65]
	v_add_f32_e32 v130, v155, v177
	v_add_f32_e32 v130, v156, v130
	v_add_f32_e32 v130, v157, v130
	v_add_f32_e32 v130, v158, v130
	v_add_f32_e32 v130, v159, v130
	v_add_f32_e32 v130, v160, v130
	v_add_f32_e32 v130, v161, v130
	v_mfma_f32_32x32x16_bf16 v[66:81], v[134:137], v[106:109], v[66:81]
	v_add_f32_e32 v130, v162, v130
	v_add_f32_e32 v130, v163, v130
	v_add_f32_e32 v130, v164, v130
	v_add_f32_e32 v130, v165, v130
	v_add_f32_e32 v130, v166, v130
	v_add_f32_e32 v130, v167, v130
	v_add_f32_e32 v130, v168, v130
	v_mfma_f32_32x32x16_bf16 v[66:81], v[138:141], v[102:105], v[66:81]
	v_add_f32_e32 v130, v169, v130
	v_add_f32_e32 v130, v170, v130
	v_add_f32_e32 v130, v171, v130
	v_add_f32_e32 v130, v172, v130
	v_add_f32_e32 v130, v173, v130
	v_add_f32_e32 v130, v174, v130
	v_add_f32_e32 v177, v175, v130
	v_mfma_f32_32x32x16_bf16 v[66:81], v[142:145], v[98:101], v[66:81]
	v_cvt_pk_bf16_f32 v130, v129, v146
	v_cvt_pk_bf16_f32 v131, v147, v148
	v_cvt_pk_bf16_f32 v132, v149, v150
	v_cvt_pk_bf16_f32 v133, v151, v152
	v_cvt_pk_bf16_f32 v134, v153, v154
	v_cvt_pk_bf16_f32 v135, v155, v156
	v_cvt_pk_bf16_f32 v136, v157, v158
	v_cvt_pk_bf16_f32 v137, v159, v160
	v_cvt_pk_bf16_f32 v138, v161, v162
	v_cvt_pk_bf16_f32 v139, v163, v164
	v_cvt_pk_bf16_f32 v140, v165, v166
	v_cvt_pk_bf16_f32 v141, v167, v168
	v_cvt_pk_bf16_f32 v142, v169, v170
	v_cvt_pk_bf16_f32 v143, v171, v172
	v_cvt_pk_bf16_f32 v144, v173, v174
	v_cvt_pk_bf16_f32 v145, v175, v176
	v_add_u32_e32 v129, s53, v125
	ds_read_b64_tr_b16 v[146:147], v129 offset:8192
	ds_read_b64_tr_b16 v[148:149], v129 offset:8704
	ds_read_b64_tr_b16 v[150:151], v129 offset:12288
	s_waitcnt lgkmcnt(1)
	v_mfma_f32_32x32x16_bf16 v[18:33], v[146:149], v[130:133], v[18:33]
	ds_read_b64_tr_b16 v[152:153], v129 offset:12800
	ds_read_b64_tr_b16 v[146:147], v129 offset:9216
	s_waitcnt lgkmcnt(1)
	v_mfma_f32_32x32x16_bf16 v[2:17], v[150:153], v[130:133], v[2:17]
	ds_read_b64_tr_b16 v[148:149], v129 offset:9728
	ds_read_b64_tr_b16 v[130:131], v129 offset:13312
	s_waitcnt lgkmcnt(1)
	v_mfma_f32_32x32x16_bf16 v[18:33], v[146:149], v[134:137], v[18:33]
	ds_read_b64_tr_b16 v[132:133], v129 offset:13824
	ds_read_b64_tr_b16 v[146:147], v129 offset:10240
	s_waitcnt lgkmcnt(1)
	v_mfma_f32_32x32x16_bf16 v[2:17], v[130:133], v[134:137], v[2:17]
	ds_read_b64_tr_b16 v[148:149], v129 offset:10752
	ds_read_b64_tr_b16 v[130:131], v129 offset:11264
	ds_read_b64_tr_b16 v[132:133], v129 offset:11776
	ds_read_b64_tr_b16 v[134:135], v129 offset:14336
	ds_read_b64_tr_b16 v[136:137], v129 offset:14848
	ds_read_b64_tr_b16 v[150:151], v129 offset:15360
	ds_read_b64_tr_b16 v[152:153], v129 offset:15872
	v_max_f32_e32 v129, v67, v67
	s_waitcnt lgkmcnt(6)
	v_mfma_f32_32x32x16_bf16 v[18:33], v[146:149], v[138:141], v[18:33]
	v_max_f32_e32 v146, v83, v83
	v_max_f32_e32 v129, v146, v129
	v_max3_f32 v146, v82, v66, v84
	v_max3_f32 v129, v129, v85, v69
	v_max3_f32 v146, v146, v68, v86
	v_max3_f32 v129, v129, v87, v71
	v_max3_f32 v129, v129, v89, v73
	s_waitcnt lgkmcnt(2)
	v_mfma_f32_32x32x16_bf16 v[2:17], v[134:137], v[138:141], v[2:17]
	v_max3_f32 v134, v146, v70, v88
	v_max3_f32 v134, v134, v72, v90
	v_max3_f32 v129, v129, v91, v75
	v_max3_f32 v134, v134, v74, v92
	v_max3_f32 v129, v129, v93, v77
	v_max3_f32 v134, v134, v76, v94
	v_max3_f32 v129, v129, v95, v79
	v_mfma_f32_32x32x16_bf16 v[18:33], v[130:133], v[142:145], v[18:33]
	v_max3_f32 v130, v134, v78, v96
	v_max3_f32 v129, v129, v97, v81
	v_add_f32_e32 v131, v176, v177
	v_max3_f32 v129, v130, v80, v129
	v_add_f32_e32 v128, v128, v131
	v_cmp_lt_f32_e32 vcc, s33, v129
	s_waitcnt lgkmcnt(0)
	v_mfma_f32_32x32x16_bf16 v[2:17], v[150:153], v[142:145], v[2:17]
	s_cbranch_vccz .LBB0_404
	v_mov_b32_e32 v34, v129
	s_nop 1
	v_permlane32_swap_b32 v129, v34
	s_nop 1
	s_nop 0
	v_max3_f32 v36, v129, v34, 0
	v_exp_f32_e64 v38, -v36
	v_add_f32_e32 v127, v127, v36
	v_xor_b32_e32 v34, 0x80000000, v127
	v_pk_add_f32 v[82:83], v[82:83], v[36:37] op_sel_hi:[1,0] neg_lo:[0,1] neg_hi:[0,1]
	v_pk_add_f32 v[84:85], v[84:85], v[36:37] op_sel_hi:[1,0] neg_lo:[0,1] neg_hi:[0,1]
	v_pk_add_f32 v[86:87], v[86:87], v[36:37] op_sel_hi:[1,0] neg_lo:[0,1] neg_hi:[0,1]
	v_pk_add_f32 v[88:89], v[88:89], v[36:37] op_sel_hi:[1,0] neg_lo:[0,1] neg_hi:[0,1]
	v_pk_add_f32 v[90:91], v[90:91], v[36:37] op_sel_hi:[1,0] neg_lo:[0,1] neg_hi:[0,1]
	v_pk_add_f32 v[92:93], v[92:93], v[36:37] op_sel_hi:[1,0] neg_lo:[0,1] neg_hi:[0,1]
	v_pk_add_f32 v[94:95], v[94:95], v[36:37] op_sel_hi:[1,0] neg_lo:[0,1] neg_hi:[0,1]
	v_pk_add_f32 v[96:97], v[96:97], v[36:37] op_sel_hi:[1,0] neg_lo:[0,1] neg_hi:[0,1]
	v_sub_f32_e32 v81, v81, v36
	v_sub_f32_e32 v80, v80, v36
	v_sub_f32_e32 v79, v79, v36
	v_sub_f32_e32 v78, v78, v36
	v_sub_f32_e32 v77, v77, v36
	v_sub_f32_e32 v76, v76, v36
	v_sub_f32_e32 v75, v75, v36
	v_sub_f32_e32 v74, v74, v36
	v_sub_f32_e32 v73, v73, v36
	v_sub_f32_e32 v72, v72, v36
	v_sub_f32_e32 v71, v71, v36
	v_sub_f32_e32 v70, v70, v36
	v_sub_f32_e32 v69, v69, v36
	v_sub_f32_e32 v68, v68, v36
	v_sub_f32_e32 v67, v67, v36
	v_sub_f32_e32 v66, v66, v36
	v_pk_mul_f32 v[32:33], v[32:33], v[38:39] op_sel_hi:[1,0]
	v_pk_mul_f32 v[30:31], v[30:31], v[38:39] op_sel_hi:[1,0]
	v_pk_mul_f32 v[28:29], v[28:29], v[38:39] op_sel_hi:[1,0]
	v_pk_mul_f32 v[26:27], v[26:27], v[38:39] op_sel_hi:[1,0]
	v_pk_mul_f32 v[24:25], v[24:25], v[38:39] op_sel_hi:[1,0]
	v_pk_mul_f32 v[22:23], v[22:23], v[38:39] op_sel_hi:[1,0]
	v_pk_mul_f32 v[20:21], v[20:21], v[38:39] op_sel_hi:[1,0]
	v_pk_mul_f32 v[18:19], v[18:19], v[38:39] op_sel_hi:[1,0]
	v_pk_mul_f32 v[16:17], v[16:17], v[38:39] op_sel_hi:[1,0]
	v_pk_mul_f32 v[14:15], v[14:15], v[38:39] op_sel_hi:[1,0]
	v_pk_mul_f32 v[12:13], v[12:13], v[38:39] op_sel_hi:[1,0]
	v_pk_mul_f32 v[10:11], v[10:11], v[38:39] op_sel_hi:[1,0]
	v_pk_mul_f32 v[8:9], v[8:9], v[38:39] op_sel_hi:[1,0]
	v_pk_mul_f32 v[6:7], v[6:7], v[38:39] op_sel_hi:[1,0]
	v_pk_mul_f32 v[4:5], v[4:5], v[38:39] op_sel_hi:[1,0]
	v_pk_mul_f32 v[2:3], v[2:3], v[38:39] op_sel_hi:[1,0]
	v_mul_f32_e32 v128, v128, v38
	v_mov_b32_e32 v35, v34
	v_mov_b32_e32 v36, v34
	v_mov_b32_e32 v37, v34
	v_mov_b32_e32 v38, v34
	v_mov_b32_e32 v39, v34
	v_mov_b32_e32 v40, v34
	v_mov_b32_e32 v41, v34
	v_mov_b32_e32 v42, v34
	v_mov_b32_e32 v43, v34
	v_mov_b32_e32 v44, v34
	v_mov_b32_e32 v45, v34
	v_mov_b32_e32 v46, v34
	v_mov_b32_e32 v47, v34
	v_mov_b32_e32 v48, v34
	v_mov_b32_e32 v49, v34
	v_mov_b32_e32 v50, v34
	v_mov_b32_e32 v51, v34
	v_mov_b32_e32 v52, v34
	v_mov_b32_e32 v53, v34
	v_mov_b32_e32 v54, v34
	v_mov_b32_e32 v55, v34
	v_mov_b32_e32 v56, v34
	v_mov_b32_e32 v57, v34
	v_mov_b32_e32 v58, v34
	v_mov_b32_e32 v59, v34
	v_mov_b32_e32 v60, v34
	v_mov_b32_e32 v61, v34
	v_mov_b32_e32 v62, v34
	v_mov_b32_e32 v63, v34
	v_mov_b32_e32 v64, v34
	v_mov_b32_e32 v65, v34

.LBB0_407:
	v_mov_b64_e32 v[34:35], v[50:51]
	v_mov_b64_e32 v[36:37], v[52:53]
	v_mov_b64_e32 v[38:39], v[54:55]
	v_mov_b64_e32 v[40:41], v[56:57]
	v_mov_b64_e32 v[42:43], v[58:59]
	v_mov_b64_e32 v[44:45], v[60:61]
	v_mov_b64_e32 v[46:47], v[62:63]
	v_mov_b64_e32 v[48:49], v[64:65]
	v_add_u32_e32 v90, s57, v126
	ds_read_b128 v[82:85], v90
	ds_read_b128 v[86:89], v90 offset:2048
	v_exp_f32_e32 v91, v66
	v_exp_f32_e32 v92, v67
	v_exp_f32_e32 v93, v68
	v_exp_f32_e32 v94, v69
	ds_read_b128 v[66:69], v90 offset:4096
	v_exp_f32_e32 v95, v70
	v_exp_f32_e32 v96, v71
	s_waitcnt lgkmcnt(2)
	v_mfma_f32_32x32x16_bf16 v[50:65], v[82:85], v[110:113], v[34:49]
	v_exp_f32_e32 v97, v72
	v_exp_f32_e32 v126, v73
	ds_read_b128 v[70:73], v90 offset:6144
	v_exp_f32_e32 v127, v74
	v_exp_f32_e32 v145, v79
	v_exp_f32_e32 v146, v80
	v_exp_f32_e32 v147, v81
	s_waitcnt lgkmcnt(2)
	v_mfma_f32_32x32x16_bf16 v[50:65], v[86:89], v[106:109], v[50:65]
	v_exp_f32_e32 v86, v75
	v_exp_f32_e32 v87, v76
	v_exp_f32_e32 v88, v77
	v_exp_f32_e32 v89, v78
	v_add_f32_e32 v148, v129, v131
	s_waitcnt lgkmcnt(1)
	v_mfma_f32_32x32x16_bf16 v[50:65], v[66:69], v[102:105], v[50:65]
	ds_read_b128 v[66:69], v90 offset:512
	ds_read_b128 v[74:77], v90 offset:2560
	ds_read_b128 v[78:81], v90 offset:4608
	ds_read_b128 v[82:85], v90 offset:6656
	v_add_f32_e32 v90, v132, v148
	s_waitcnt lgkmcnt(3)
	v_mfma_f32_32x32x16_bf16 v[34:49], v[66:69], v[110:113], v[34:49]
	v_cvt_pk_bf16_f32 v67, v132, v135
	v_cvt_pk_bf16_f32 v68, v136, v139
	v_cvt_pk_bf16_f32 v69, v140, v143
	v_mfma_f32_32x32x16_bf16 v[50:65], v[70:73], v[98:101], v[50:65]
	v_add_f32_e32 v70, v135, v90
	v_add_f32_e32 v70, v136, v70
	v_add_f32_e32 v70, v139, v70
	v_add_f32_e32 v70, v140, v70
	v_add_f32_e32 v70, v143, v70
	v_add_f32_e32 v70, v130, v70
	v_add_f32_e32 v70, v133, v70
	s_waitcnt lgkmcnt(2)
	v_mfma_f32_32x32x16_bf16 v[34:49], v[74:77], v[106:109], v[34:49]
	v_add_f32_e32 v66, v134, v70
	v_add_f32_e32 v66, v137, v66
	v_add_f32_e32 v66, v138, v66
	v_add_f32_e32 v66, v141, v66
	v_add_f32_e32 v66, v142, v66
	v_add_f32_e32 v66, v144, v66
	v_add_f32_e32 v66, v91, v66
	s_waitcnt lgkmcnt(1)
	v_mfma_f32_32x32x16_bf16 v[34:49], v[78:81], v[102:105], v[34:49]
	v_add_f32_e32 v66, v92, v66
	v_add_f32_e32 v66, v93, v66
	v_add_f32_e32 v66, v94, v66
	v_add_f32_e32 v66, v95, v66
	v_add_f32_e32 v66, v96, v66
	v_add_f32_e32 v66, v97, v66
	v_add_f32_e32 v66, v126, v66
	s_waitcnt lgkmcnt(0)
	v_mfma_f32_32x32x16_bf16 v[34:49], v[82:85], v[98:101], v[34:49]
	v_add_f32_e32 v66, v127, v66
	v_add_f32_e32 v66, v86, v66
	v_add_f32_e32 v66, v87, v66
	v_add_f32_e32 v66, v88, v66
	v_add_f32_e32 v66, v89, v66
	v_add_f32_e32 v66, v145, v66
	v_add_f32_e32 v90, v146, v66
	v_cvt_pk_bf16_f32 v66, v129, v131
	v_cvt_pk_bf16_f32 v70, v130, v133
	v_cvt_pk_bf16_f32 v71, v134, v137
	v_cvt_pk_bf16_f32 v72, v138, v141
	v_cvt_pk_bf16_f32 v73, v142, v144
	v_cvt_pk_bf16_f32 v74, v91, v92
	v_cvt_pk_bf16_f32 v75, v93, v94
	v_cvt_pk_bf16_f32 v76, v95, v96
	v_cvt_pk_bf16_f32 v77, v97, v126
	v_cvt_pk_bf16_f32 v78, v127, v86
	v_cvt_pk_bf16_f32 v79, v87, v88
	v_cvt_pk_bf16_f32 v80, v89, v145
	v_cvt_pk_bf16_f32 v81, v146, v147
	v_add_u32_e32 v91, s54, v125
	ds_read_b64_tr_b16 v[82:83], v91 offset:8192
	ds_read_b64_tr_b16 v[84:85], v91 offset:8704
	ds_read_b64_tr_b16 v[86:87], v91 offset:12288
	s_waitcnt lgkmcnt(1)
	v_mfma_f32_32x32x16_bf16 v[18:33], v[82:85], v[66:69], v[18:33]
	ds_read_b64_tr_b16 v[88:89], v91 offset:12800
	ds_read_b64_tr_b16 v[82:83], v91 offset:9216
	s_waitcnt lgkmcnt(1)
	v_mfma_f32_32x32x16_bf16 v[2:17], v[86:89], v[66:69], v[2:17]
	ds_read_b64_tr_b16 v[84:85], v91 offset:9728
	ds_read_b64_tr_b16 v[66:67], v91 offset:13312
	s_waitcnt lgkmcnt(1)
	v_mfma_f32_32x32x16_bf16 v[18:33], v[82:85], v[70:73], v[18:33]
	ds_read_b64_tr_b16 v[68:69], v91 offset:13824
	ds_read_b64_tr_b16 v[82:83], v91 offset:10240
	s_waitcnt lgkmcnt(1)
	v_mfma_f32_32x32x16_bf16 v[2:17], v[66:69], v[70:73], v[2:17]
	ds_read_b64_tr_b16 v[84:85], v91 offset:10752
	ds_read_b64_tr_b16 v[66:67], v91 offset:11264
	ds_read_b64_tr_b16 v[68:69], v91 offset:11776
	ds_read_b64_tr_b16 v[70:71], v91 offset:14336
	ds_read_b64_tr_b16 v[72:73], v91 offset:14848
	ds_read_b64_tr_b16 v[86:87], v91 offset:15360
	ds_read_b64_tr_b16 v[88:89], v91 offset:15872
	s_waitcnt lgkmcnt(6)
	v_mfma_f32_32x32x16_bf16 v[18:33], v[82:85], v[74:77], v[18:33]
	v_max_f32_e32 v82, v35, v35
	v_max_f32_e32 v83, v51, v51
	v_max_f32_e32 v82, v83, v82
	v_max3_f32 v83, v50, v34, v52
	v_max3_f32 v82, v82, v53, v37
	v_max3_f32 v83, v83, v36, v54
	v_max3_f32 v82, v82, v55, v39
	s_waitcnt lgkmcnt(2)
	v_mfma_f32_32x32x16_bf16 v[2:17], v[70:73], v[74:77], v[2:17]
	v_max3_f32 v70, v83, v38, v56
	v_max3_f32 v71, v82, v57, v41
	v_max3_f32 v70, v70, v40, v58
	v_max3_f32 v71, v71, v59, v43
	v_max3_f32 v70, v70, v42, v60
	v_max3_f32 v71, v71, v61, v45
	v_max3_f32 v70, v70, v44, v62
	v_mfma_f32_32x32x16_bf16 v[18:33], v[66:69], v[78:81], v[18:33]
	v_max3_f32 v66, v71, v63, v47
	v_max3_f32 v67, v70, v46, v64
	v_max3_f32 v68, v66, v65, v49
	v_add_f32_e32 v66, v147, v90
	v_max3_f32 v67, v67, v48, v68
	v_add_f32_e32 v66, v128, v66
	v_cmp_lt_f32_e32 vcc, s33, v67
	s_waitcnt lgkmcnt(0)
	v_mfma_f32_32x32x16_bf16 v[2:17], v[86:89], v[78:81], v[2:17]
	s_cbranch_vccz .LBB0_409
	v_mov_b32_e32 v68, v67
	s_nop 1
	v_permlane32_swap_b32 v67, v68
	s_nop 1
	s_nop 0
	v_max3_f32 v68, v67, v68, 0
	v_exp_f32_e64 v70, -v68
	v_pk_add_f32 v[50:51], v[50:51], v[68:69] op_sel_hi:[1,0] neg_lo:[0,1] neg_hi:[0,1]
	v_pk_add_f32 v[52:53], v[52:53], v[68:69] op_sel_hi:[1,0] neg_lo:[0,1] neg_hi:[0,1]
	v_pk_add_f32 v[54:55], v[54:55], v[68:69] op_sel_hi:[1,0] neg_lo:[0,1] neg_hi:[0,1]
	v_pk_add_f32 v[56:57], v[56:57], v[68:69] op_sel_hi:[1,0] neg_lo:[0,1] neg_hi:[0,1]
	v_pk_add_f32 v[58:59], v[58:59], v[68:69] op_sel_hi:[1,0] neg_lo:[0,1] neg_hi:[0,1]
	v_pk_add_f32 v[60:61], v[60:61], v[68:69] op_sel_hi:[1,0] neg_lo:[0,1] neg_hi:[0,1]
	v_pk_add_f32 v[62:63], v[62:63], v[68:69] op_sel_hi:[1,0] neg_lo:[0,1] neg_hi:[0,1]
	v_pk_add_f32 v[64:65], v[64:65], v[68:69] op_sel_hi:[1,0] neg_lo:[0,1] neg_hi:[0,1]
	v_sub_f32_e32 v49, v49, v68
	v_sub_f32_e32 v48, v48, v68
	v_sub_f32_e32 v47, v47, v68
	v_sub_f32_e32 v46, v46, v68
	v_sub_f32_e32 v45, v45, v68
	v_sub_f32_e32 v44, v44, v68
	v_sub_f32_e32 v43, v43, v68
	v_sub_f32_e32 v42, v42, v68
	v_sub_f32_e32 v41, v41, v68
	v_sub_f32_e32 v40, v40, v68
	v_sub_f32_e32 v39, v39, v68
	v_sub_f32_e32 v38, v38, v68
	v_sub_f32_e32 v37, v37, v68
	v_sub_f32_e32 v36, v36, v68
	v_sub_f32_e32 v35, v35, v68
	v_sub_f32_e32 v34, v34, v68
	v_pk_mul_f32 v[32:33], v[32:33], v[70:71] op_sel_hi:[1,0]
	v_pk_mul_f32 v[30:31], v[30:31], v[70:71] op_sel_hi:[1,0]
	v_pk_mul_f32 v[28:29], v[28:29], v[70:71] op_sel_hi:[1,0]
	v_pk_mul_f32 v[26:27], v[26:27], v[70:71] op_sel_hi:[1,0]
	v_pk_mul_f32 v[24:25], v[24:25], v[70:71] op_sel_hi:[1,0]
	v_pk_mul_f32 v[22:23], v[22:23], v[70:71] op_sel_hi:[1,0]
	v_pk_mul_f32 v[20:21], v[20:21], v[70:71] op_sel_hi:[1,0]
	v_pk_mul_f32 v[18:19], v[18:19], v[70:71] op_sel_hi:[1,0]
	v_pk_mul_f32 v[16:17], v[16:17], v[70:71] op_sel_hi:[1,0]
	v_pk_mul_f32 v[14:15], v[14:15], v[70:71] op_sel_hi:[1,0]
	v_pk_mul_f32 v[12:13], v[12:13], v[70:71] op_sel_hi:[1,0]
	v_pk_mul_f32 v[10:11], v[10:11], v[70:71] op_sel_hi:[1,0]
	v_pk_mul_f32 v[8:9], v[8:9], v[70:71] op_sel_hi:[1,0]
	v_pk_mul_f32 v[6:7], v[6:7], v[70:71] op_sel_hi:[1,0]
	v_pk_mul_f32 v[4:5], v[4:5], v[70:71] op_sel_hi:[1,0]
	v_pk_mul_f32 v[2:3], v[2:3], v[70:71] op_sel_hi:[1,0]
	v_mul_f32_e32 v66, v66, v70

	.amdhsa_kernel _Z10fwd_kernel4Args
		.amdhsa_group_segment_fixed_size 0
		.amdhsa_private_segment_fixed_size 0
		.amdhsa_kernarg_size 400
		.amdhsa_user_sgpr_count 2
		.amdhsa_user_sgpr_dispatch_ptr 0
		.amdhsa_user_sgpr_queue_ptr 0
		.amdhsa_user_sgpr_kernarg_segment_ptr 1
		.amdhsa_user_sgpr_dispatch_id 0
		.amdhsa_user_sgpr_kernarg_preload_length 0
		.amdhsa_user_sgpr_kernarg_preload_offset 0
		.amdhsa_user_sgpr_private_segment_size 0
		.amdhsa_uses_dynamic_stack 0
		.amdhsa_enable_private_segment 0
		.amdhsa_system_sgpr_workgroup_id_x 1
		.amdhsa_system_sgpr_workgroup_id_y 0
		.amdhsa_system_sgpr_workgroup_id_z 0
		.amdhsa_system_sgpr_workgroup_info 0
		.amdhsa_system_vgpr_workitem_id 2
		.amdhsa_next_free_vgpr 238
		.amdhsa_next_free_sgpr 100
		.amdhsa_accum_offset 240
		.amdhsa_reserve_vcc 1
		.amdhsa_float_round_mode_32 0
		.amdhsa_float_round_mode_16_64 0
		.amdhsa_float_denorm_mode_32 3
		.amdhsa_float_denorm_mode_16_64 3
		.amdhsa_dx10_clamp 1
		.amdhsa_ieee_mode 1
		.amdhsa_fp16_overflow 0
		.amdhsa_tg_split 0
		.amdhsa_exception_fp_ieee_invalid_op 0
		.amdhsa_exception_fp_denorm_src 0
		.amdhsa_exception_fp_ieee_div_zero 0
		.amdhsa_exception_fp_ieee_overflow 0
		.amdhsa_exception_fp_ieee_underflow 0
		.amdhsa_exception_fp_ieee_inexact 0
		.amdhsa_exception_int_div_zero 0
	.end_amdhsa_kernel

amdhsa.kernels:
  - .agpr_count:     0
    .args:
      - .offset:         0
        .size:           144
        .value_kind:     by_value
      - .offset:         144
        .size:           4
        .value_kind:     hidden_block_count_x
      - .offset:         148
        .size:           4
        .value_kind:     hidden_block_count_y
      - .offset:         152
        .size:           4
        .value_kind:     hidden_block_count_z
      - .offset:         156
        .size:           2
        .value_kind:     hidden_group_size_x
      - .offset:         158
        .size:           2
        .value_kind:     hidden_group_size_y
      - .offset:         160
        .size:           2
        .value_kind:     hidden_group_size_z
      - .offset:         162
        .size:           2
        .value_kind:     hidden_remainder_x
      - .offset:         164
        .size:           2
        .value_kind:     hidden_remainder_y
      - .offset:         166
        .size:           2
        .value_kind:     hidden_remainder_z
      - .offset:         184
        .size:           8
        .value_kind:     hidden_global_offset_x
      - .offset:         192
        .size:           8
        .value_kind:     hidden_global_offset_y
      - .offset:         200
        .size:           8
        .value_kind:     hidden_global_offset_z
      - .offset:         208
        .size:           2
        .value_kind:     hidden_grid_dims
      - .offset:         232
        .size:           8
        .value_kind:     hidden_multigrid_sync_arg
      - .offset:         264
        .size:           4
        .value_kind:     hidden_dynamic_lds_size
    .group_segment_fixed_size: 0
    .kernarg_segment_align: 8
    .kernarg_segment_size: 400
    .language:       OpenCL C
    .language_version:
      - 2
      - 0
    .max_flat_workgroup_size: 512
    .name:           _Z10fwd_kernel4Args
    .private_segment_fixed_size: 0
    .sgpr_count:     106
    .sgpr_spill_count: 216
    .symbol:         _Z10fwd_kernel4Args.kd
    .uniform_work_group_size: 1
    .uses_dynamic_stack: false
    .vgpr_count:     238
    .vgpr_spill_count: 0
    .wavefront_size: 64
